# code placement: the seven GEMM K-loop heads aligned to 64 bytes
# speedup vs baseline: 1.0071x; 1.0071x over previous
;     __device__ bool next(int i, Unit& u) const { if (i > 1 || !so.next(0, u)) return false; if (i == 1) { u.pm += 64; u.pn += 4; } return true; }
; template <class Epi, class Sched, bool ALIGN_EPI = false, bool SP2 = false>
; __device__ __forceinline__ void gemm_phase(PG8_LAS unsigned char* lds, const Gemm g, const Sched& S, const Epi& E) {
;     ...
;         const bool has_next = S.next(ui + 1, nxt);
;         const char* nA = has_next ? (const char*)g.A + (size_t)nxt.pm * tstep : cA; const char* nB = has_next ? (const char*)g.Bt + (size_t)nxt.pn * tstep : cB;
;         for (int t = 0; t < nt; t += 2) {
;             const bool last = (t == nt - 2);
;             const char* a1 = cA + (size_t)(t + 1) * kstep;
;             const char* a2 = last ? nA : cA + (size_t)(t + 2) * kstep; const char* b2 = last ? nB : cB + (size_t)(t + 2) * kstep;
;             const char* a3 = a2 + kstep; const char* b3 = b2 + kstep;
;     ...
;         for (int a = 0; a < 2; ++a)
; #pragma unroll
;             for (int b = 0; b < 2; ++b)
; #pragma unroll
;                 for (int m = 0; m < 4; ++m)
; #pragma unroll
;                     for (int n = 0; n < 2; ++n) acc[a][b][m][n] = (f32x4){0.f, 0.f, 0.f, 0.f};
.LBB0_193:
	s_ashr_i32 s19, s18, 31
	s_lshl_b64 s[20:21], s[18:19], 19
	s_add_u32 s20, s30, s20
	s_addc_u32 s21, s31, s21
	s_and_b64 s[34:35], s[4:5], exec
	s_cselect_b32 s19, s21, s39
	s_cselect_b32 s72, s20, s38
	s_ashr_i32 s17, s16, 31
	s_lshl_b64 s[34:35], s[16:17], 19
	s_add_u32 s34, s88, s34
	s_addc_u32 s35, s89, s35
	s_and_b64 s[52:53], s[4:5], exec
	s_cselect_b32 s17, s35, s41
	s_cselect_b32 s73, s34, s40
	s_add_u32 s38, s38, 0x40080
	s_addc_u32 s39, s39, 0
	s_add_u32 s76, s40, 0x100
	v_mov_b32_e32 v0, 0
	s_addc_u32 s77, s41, 0
	s_mov_b32 s78, -2
	v_mov_b32_e32 v1, v0
	v_mov_b64_e32 v[2:3], 0
	v_mov_b64_e32 v[8:9], 0
	v_mov_b64_e32 v[10:11], 0
	v_mov_b64_e32 v[16:17], 0
	v_mov_b64_e32 v[18:19], 0
	v_mov_b64_e32 v[24:25], 0
	v_mov_b64_e32 v[26:27], 0
	v_mov_b64_e32 v[32:33], 0
	v_mov_b64_e32 v[34:35], 0
	v_mov_b64_e32 v[40:41], 0
	v_mov_b64_e32 v[42:43], 0
	v_mov_b64_e32 v[48:49], 0
	v_mov_b64_e32 v[50:51], 0
	v_mov_b64_e32 v[56:57], 0
	v_mov_b64_e32 v[58:59], 0
	v_mov_b64_e32 v[4:5], 0
	v_mov_b64_e32 v[6:7], 0
	v_mov_b64_e32 v[12:13], 0
	v_mov_b64_e32 v[14:15], 0
	v_mov_b64_e32 v[20:21], 0
	v_mov_b64_e32 v[22:23], 0
	v_mov_b64_e32 v[28:29], 0
	v_mov_b64_e32 v[30:31], 0
	v_mov_b64_e32 v[36:37], 0
	v_mov_b64_e32 v[38:39], 0
	v_mov_b64_e32 v[44:45], 0
	v_mov_b64_e32 v[46:47], 0
	v_mov_b64_e32 v[52:53], 0
	v_mov_b64_e32 v[54:55], 0
	v_mov_b64_e32 v[60:61], 0
	v_mov_b64_e32 v[62:63], 0
	v_mov_b64_e32 v[64:65], 0
	v_mov_b64_e32 v[66:67], 0
	v_mov_b64_e32 v[72:73], 0
	v_mov_b64_e32 v[74:75], 0
	v_mov_b64_e32 v[80:81], 0
	v_mov_b64_e32 v[82:83], 0
	v_mov_b64_e32 v[88:89], 0
	v_mov_b64_e32 v[90:91], 0
	v_mov_b64_e32 v[96:97], 0
	v_mov_b64_e32 v[98:99], 0
	v_mov_b64_e32 v[104:105], 0
	v_mov_b64_e32 v[106:107], 0
	v_mov_b64_e32 v[112:113], 0
	v_mov_b64_e32 v[114:115], 0
	v_mov_b64_e32 v[120:121], 0
	v_mov_b64_e32 v[122:123], 0
	v_mov_b64_e32 v[68:69], 0
	v_mov_b64_e32 v[70:71], 0
	v_mov_b64_e32 v[76:77], 0
	v_mov_b64_e32 v[78:79], 0
	v_mov_b64_e32 v[84:85], 0
	v_mov_b64_e32 v[86:87], 0
	v_mov_b64_e32 v[92:93], 0
	v_mov_b64_e32 v[94:95], 0
	v_mov_b64_e32 v[100:101], 0
	v_mov_b64_e32 v[102:103], 0
	v_mov_b64_e32 v[108:109], 0
	v_mov_b64_e32 v[110:111], 0
	v_mov_b64_e32 v[116:117], 0
	v_mov_b64_e32 v[118:119], 0
	v_mov_b64_e32 v[124:125], 0
	v_mov_b64_e32 v[126:127], 0
	.p2align	6

; template <class Epi, class Sched, bool ALIGN_EPI = false, bool SP2 = false>
; __device__ __forceinline__ void gemm_phase(PG8_LAS unsigned char* lds, const Gemm g, const Sched& S, const Epi& E) {
;     ...
;         for (int t = 0; t < nt; t += 2) {
;             const bool last = (t == nt - 2);
;             const char* a1 = cA + (size_t)(t + 1) * kstep;
;             const char* a2 = last ? nA : cA + (size_t)(t + 2) * kstep; const char* b2 = last ? nB : cB + (size_t)(t + 2) * kstep;
;             const char* a3 = a2 + kstep; const char* b3 = b2 + kstep;
;     ...
;         for (int a = 0; a < 2; ++a)
; #pragma unroll
;             for (int b = 0; b < 2; ++b)
; #pragma unroll
;                 for (int m = 0; m < 4; ++m)
; #pragma unroll
;                     for (int n = 0; n < 2; ++n) acc[a][b][m][n] = (f32x4){0.f, 0.f, 0.f, 0.f};
.LBB0_288:
	s_add_u32 s22, s22, 0xb0080
	s_addc_u32 s23, s23, 0
	s_add_u32 s66, s34, 0x100
	v_mov_b32_e32 v0, 0
	s_addc_u32 s67, s35, 0
	s_mov_b32 s70, -2
	s_waitcnt lgkmcnt(0)
	v_mov_b32_e32 v1, v0
	v_mov_b64_e32 v[2:3], 0
	v_mov_b64_e32 v[4:5], 0
	v_mov_b64_e32 v[6:7], 0
	v_mov_b64_e32 v[16:17], 0
	v_mov_b64_e32 v[18:19], 0
	v_mov_b64_e32 v[20:21], 0
	v_mov_b64_e32 v[22:23], 0
	v_mov_b64_e32 v[32:33], 0
	v_mov_b64_e32 v[34:35], 0
	v_mov_b64_e32 v[36:37], 0
	v_mov_b64_e32 v[38:39], 0
	v_mov_b64_e32 v[48:49], 0
	v_mov_b64_e32 v[50:51], 0
	v_mov_b64_e32 v[52:53], 0
	v_mov_b64_e32 v[54:55], 0
	v_mov_b64_e32 v[8:9], 0
	v_mov_b64_e32 v[10:11], 0
	v_mov_b64_e32 v[12:13], 0
	v_mov_b64_e32 v[14:15], 0
	v_mov_b64_e32 v[24:25], 0
	v_mov_b64_e32 v[26:27], 0
	v_mov_b64_e32 v[28:29], 0
	v_mov_b64_e32 v[30:31], 0
	v_mov_b64_e32 v[40:41], 0
	v_mov_b64_e32 v[42:43], 0
	v_mov_b64_e32 v[44:45], 0
	v_mov_b64_e32 v[46:47], 0
	v_mov_b64_e32 v[56:57], 0
	v_mov_b64_e32 v[58:59], 0
	v_mov_b64_e32 v[60:61], 0
	v_mov_b64_e32 v[62:63], 0
	v_mov_b64_e32 v[64:65], 0
	v_mov_b64_e32 v[66:67], 0
	v_mov_b64_e32 v[68:69], 0
	v_mov_b64_e32 v[70:71], 0
	v_mov_b64_e32 v[80:81], 0
	v_mov_b64_e32 v[82:83], 0
	v_mov_b64_e32 v[84:85], 0
	v_mov_b64_e32 v[86:87], 0
	v_mov_b64_e32 v[96:97], 0
	v_mov_b64_e32 v[98:99], 0
	v_mov_b64_e32 v[100:101], 0
	v_mov_b64_e32 v[102:103], 0
	v_mov_b64_e32 v[112:113], 0
	v_mov_b64_e32 v[114:115], 0
	v_mov_b64_e32 v[116:117], 0
	v_mov_b64_e32 v[118:119], 0
	v_mov_b64_e32 v[72:73], 0
	v_mov_b64_e32 v[74:75], 0
	v_mov_b64_e32 v[76:77], 0
	v_mov_b64_e32 v[78:79], 0
	v_mov_b64_e32 v[88:89], 0
	v_mov_b64_e32 v[90:91], 0
	v_mov_b64_e32 v[92:93], 0
	v_mov_b64_e32 v[94:95], 0
	v_mov_b64_e32 v[104:105], 0
	v_mov_b64_e32 v[106:107], 0
	v_mov_b64_e32 v[108:109], 0
	v_mov_b64_e32 v[110:111], 0
	v_mov_b64_e32 v[120:121], 0
	v_mov_b64_e32 v[122:123], 0
	v_mov_b64_e32 v[124:125], 0
	v_mov_b64_e32 v[126:127], 0
	.p2align	6

;     __device__ bool next(int i, Unit& u) const { if (i > 1 || !so.next(0, u)) return false; if (i == 1) { u.pm += 64; u.pn += 4; } return true; }
; template <class Epi, class Sched, bool ALIGN_EPI = false, bool SP2 = false>
; __device__ __forceinline__ void gemm_phase(PG8_LAS unsigned char* lds, const Gemm g, const Sched& S, const Epi& E) {
;     ...
;         const bool has_next = S.next(ui + 1, nxt);
;         const char* nA = has_next ? (const char*)g.A + (size_t)nxt.pm * tstep : cA; const char* nB = has_next ? (const char*)g.Bt + (size_t)nxt.pn * tstep : cB;
;         for (int t = 0; t < nt; t += 2) {
;             const bool last = (t == nt - 2);
;             const char* a1 = cA + (size_t)(t + 1) * kstep;
;             const char* a2 = last ? nA : cA + (size_t)(t + 2) * kstep; const char* b2 = last ? nB : cB + (size_t)(t + 2) * kstep;
;             const char* a3 = a2 + kstep; const char* b3 = b2 + kstep;
;     ...
;         for (int a = 0; a < 2; ++a)
; #pragma unroll
;             for (int b = 0; b < 2; ++b)
; #pragma unroll
;                 for (int m = 0; m < 4; ++m)
; #pragma unroll
;                     for (int n = 0; n < 2; ++n) acc[a][b][m][n] = (f32x4){0.f, 0.f, 0.f, 0.f};
.LBB0_406:
	s_ashr_i32 s41, s40, 31
	s_lshl_b64 s[44:45], s[40:41], 19
	s_add_u32 s44, s84, s44
	s_addc_u32 s45, s85, s45
	s_and_b64 s[46:47], s[4:5], exec
	s_cselect_b32 s7, s45, s1
	s_cselect_b32 s9, s44, s0
	s_ashr_i32 s23, s22, 31
	s_lshl_b64 s[46:47], s[22:23], 19
	s_add_u32 s46, s21, s46
	s_addc_u32 s47, s58, s47
	s_and_b64 s[52:53], s[4:5], exec
	s_cselect_b32 s12, s47, s49
	s_cselect_b32 s23, s46, s48
	s_add_u32 s0, s0, 0x40080
	s_addc_u32 s1, s1, 0
	s_add_u32 s41, s48, 0x100
	v_mov_b32_e32 v0, 0
	s_addc_u32 s54, s49, 0
	s_mov_b32 s55, -2
	v_mov_b32_e32 v1, v0
	v_mov_b64_e32 v[2:3], 0
	v_mov_b64_e32 v[4:5], 0
	v_mov_b64_e32 v[6:7], 0
	v_mov_b64_e32 v[16:17], 0
	v_mov_b64_e32 v[18:19], 0
	v_mov_b64_e32 v[20:21], 0
	v_mov_b64_e32 v[22:23], 0
	v_mov_b64_e32 v[64:65], 0
	v_mov_b64_e32 v[66:67], 0
	v_mov_b64_e32 v[68:69], 0
	v_mov_b64_e32 v[70:71], 0
	v_mov_b64_e32 v[80:81], 0
	v_mov_b64_e32 v[82:83], 0
	v_mov_b64_e32 v[84:85], 0
	v_mov_b64_e32 v[86:87], 0
	v_mov_b64_e32 v[8:9], 0
	v_mov_b64_e32 v[10:11], 0
	v_mov_b64_e32 v[12:13], 0
	v_mov_b64_e32 v[14:15], 0
	v_mov_b64_e32 v[32:33], 0
	v_mov_b64_e32 v[34:35], 0
	v_mov_b64_e32 v[40:41], 0
	v_mov_b64_e32 v[42:43], 0
	v_mov_b64_e32 v[72:73], 0
	v_mov_b64_e32 v[74:75], 0
	v_mov_b64_e32 v[76:77], 0
	v_mov_b64_e32 v[78:79], 0
	v_mov_b64_e32 v[88:89], 0
	v_mov_b64_e32 v[90:91], 0
	v_mov_b64_e32 v[92:93], 0
	v_mov_b64_e32 v[94:95], 0
	v_mov_b64_e32 v[96:97], 0
	v_mov_b64_e32 v[98:99], 0
	v_mov_b64_e32 v[100:101], 0
	v_mov_b64_e32 v[102:103], 0
	v_mov_b64_e32 v[112:113], 0
	v_mov_b64_e32 v[114:115], 0
	v_mov_b64_e32 v[116:117], 0
	v_mov_b64_e32 v[118:119], 0
	v_mov_b64_e32 v[128:129], 0
	v_mov_b64_e32 v[130:131], 0
	v_mov_b64_e32 v[132:133], 0
	v_mov_b64_e32 v[134:135], 0
	v_mov_b64_e32 v[144:145], 0
	v_mov_b64_e32 v[146:147], 0
	v_mov_b64_e32 v[148:149], 0
	v_mov_b64_e32 v[150:151], 0
	v_mov_b64_e32 v[104:105], 0
	v_mov_b64_e32 v[106:107], 0
	v_mov_b64_e32 v[108:109], 0
	v_mov_b64_e32 v[110:111], 0
	v_mov_b64_e32 v[120:121], 0
	v_mov_b64_e32 v[122:123], 0
	v_mov_b64_e32 v[124:125], 0
	v_mov_b64_e32 v[126:127], 0
	v_mov_b64_e32 v[136:137], 0
	v_mov_b64_e32 v[138:139], 0
	v_mov_b64_e32 v[140:141], 0
	v_mov_b64_e32 v[142:143], 0
	v_mov_b64_e32 v[152:153], 0
	v_mov_b64_e32 v[154:155], 0
	v_mov_b64_e32 v[156:157], 0
	v_mov_b64_e32 v[158:159], 0
	.p2align	6

;     __device__ bool next(int i, Unit& u) const { if (i > 1 || !so.next(0, u)) return false; if (i == 1) { u.pm += 64; u.pn += 4; } return true; }
; template <class Epi, class Sched, bool ALIGN_EPI = false, bool SP2 = false>
; __device__ __forceinline__ void gemm_phase(PG8_LAS unsigned char* lds, const Gemm g, const Sched& S, const Epi& E) {
;     ...
;         const bool has_next = S.next(ui + 1, nxt);
;         const char* nA = has_next ? (const char*)g.A + (size_t)nxt.pm * tstep : cA; const char* nB = has_next ? (const char*)g.Bt + (size_t)nxt.pn * tstep : cB;
;         for (int t = 0; t < nt; t += 2) {
;             const bool last = (t == nt - 2);
;             const char* a1 = cA + (size_t)(t + 1) * kstep;
;             const char* a2 = last ? nA : cA + (size_t)(t + 2) * kstep; const char* b2 = last ? nB : cB + (size_t)(t + 2) * kstep;
;             const char* a3 = a2 + kstep; const char* b3 = b2 + kstep;
;     ...
;         cur = nxt; cA = nA; cB = nB; ++ui;
.LBB0_646:
	s_ashr_i32 s15, s14, 31
	s_andn2_b64 vcc, exec, s[46:47]
	s_lshl_b64 s[20:21], s[14:15], 18
	s_add_u32 s20, s3, s20
	s_addc_u32 s21, s62, s21
	s_and_b64 s[22:23], s[46:47], exec
	s_cselect_b32 s7, s21, s41
	s_cselect_b32 s15, s20, s40
	s_ashr_i32 s17, s16, 31
	s_lshl_b64 s[22:23], s[16:17], 18
	s_add_u32 s22, s68, s22
	v_cndmask_b32_e64 v0, 0, 1, s[46:47]
	s_addc_u32 s23, s69, s23
	v_cmp_ne_u32_e64 s[4:5], 1, v0
	s_and_b64 s[46:47], s[46:47], exec
	v_mov_b64_e32 v[0:1], v[8:9]
	v_mov_b64_e32 v[4:5], v[12:13]
	v_mov_b64_e32 v[24:25], v[44:45]
	v_mov_b64_e32 v[28:29], v[40:41]
	v_mov_b64_e32 v[56:57], v[76:77]
	v_mov_b64_e32 v[60:61], v[72:73]
	v_mov_b64_e32 v[88:89], v[108:109]
	v_mov_b64_e32 v[92:93], v[104:105]
	s_cselect_b32 s17, s23, s45
	s_cselect_b32 s39, s22, s44
	s_add_u32 s40, s40, 0x20080
	v_mov_b64_e32 v[2:3], v[10:11]
	v_mov_b64_e32 v[6:7], v[14:15]
	v_mov_b64_e32 v[26:27], v[46:47]
	v_mov_b64_e32 v[30:31], v[42:43]
	v_mov_b64_e32 v[58:59], v[78:79]
	v_mov_b64_e32 v[62:63], v[74:75]
	v_mov_b64_e32 v[90:91], v[110:111]
	v_mov_b64_e32 v[94:95], v[106:107]
	v_mov_b64_e32 v[8:9], v[156:157]
	v_mov_b64_e32 v[12:13], v[152:153]
	v_mov_b64_e32 v[40:41], v[148:149]
	v_mov_b64_e32 v[44:45], v[144:145]
	v_mov_b64_e32 v[72:73], v[140:141]
	v_mov_b64_e32 v[76:77], v[136:137]
	v_mov_b64_e32 v[104:105], v[124:125]
	v_mov_b64_e32 v[108:109], v[120:121]
	s_addc_u32 s41, s41, 0
	v_mov_b64_e32 v[10:11], v[158:159]
	v_mov_b64_e32 v[14:15], v[154:155]
	v_mov_b64_e32 v[42:43], v[150:151]
	v_mov_b64_e32 v[46:47], v[146:147]
	v_mov_b64_e32 v[74:75], v[142:143]
	v_mov_b64_e32 v[78:79], v[138:139]
	v_mov_b64_e32 v[106:107], v[126:127]
	v_mov_b64_e32 v[110:111], v[122:123]
	v_mov_b64_e32 v[120:121], v[132:133]
	v_mov_b64_e32 v[124:125], v[128:129]
	v_mov_b64_e32 v[138:139], v[102:103]
	v_mov_b64_e32 v[142:143], v[98:99]
	v_mov_b64_e32 v[146:147], v[70:71]
	v_mov_b64_e32 v[150:151], v[66:67]
	v_mov_b64_e32 v[154:155], v[38:39]
	v_mov_b64_e32 v[158:159], v[34:35]
	s_add_u32 s57, s44, 0x100
	v_mov_b64_e32 v[122:123], v[134:135]
	v_mov_b64_e32 v[126:127], v[130:131]
	v_mov_b64_e32 v[136:137], v[100:101]
	v_mov_b64_e32 v[140:141], v[96:97]
	v_mov_b64_e32 v[144:145], v[68:69]
	v_mov_b64_e32 v[148:149], v[64:65]
	v_mov_b64_e32 v[152:153], v[36:37]
	v_mov_b64_e32 v[156:157], v[32:33]
	v_mov_b64_e32 v[130:131], v[118:119]
	v_mov_b64_e32 v[134:135], v[114:115]
	v_mov_b64_e32 v[98:99], v[86:87]
	v_mov_b64_e32 v[102:103], v[82:83]
	v_mov_b64_e32 v[66:67], v[54:55]
	v_mov_b64_e32 v[70:71], v[50:51]
	v_mov_b64_e32 v[34:35], v[22:23]
	v_mov_b64_e32 v[38:39], v[18:19]
	s_addc_u32 s58, s45, 0
	s_mov_b32 s59, -2
	v_mov_b64_e32 v[128:129], v[116:117]
	v_mov_b64_e32 v[132:133], v[112:113]
	v_mov_b64_e32 v[96:97], v[84:85]
	v_mov_b64_e32 v[100:101], v[80:81]
	v_mov_b64_e32 v[64:65], v[52:53]
	v_mov_b64_e32 v[68:69], v[48:49]
	v_mov_b64_e32 v[32:33], v[20:21]
	v_mov_b64_e32 v[36:37], v[16:17]
	.p2align	6

;     __device__ bool next(int i, Unit& u) const { if (i > 1 || !so.next(0, u)) return false; if (i == 1) { u.pm += 64; u.pn += 4; } return true; }
; template <class Epi, class Sched, bool ALIGN_EPI = false, bool SP2 = false>
; __device__ __forceinline__ void gemm_phase(PG8_LAS unsigned char* lds, const Gemm g, const Sched& S, const Epi& E) {
;     ...
;         const bool has_next = S.next(ui + 1, nxt);
;         const char* nA = has_next ? (const char*)g.A + (size_t)nxt.pm * tstep : cA; const char* nB = has_next ? (const char*)g.Bt + (size_t)nxt.pn * tstep : cB;
;         for (int t = 0; t < nt; t += 2) {
;             const bool last = (t == nt - 2);
;             const char* a1 = cA + (size_t)(t + 1) * kstep;
;             const char* a2 = last ? nA : cA + (size_t)(t + 2) * kstep; const char* b2 = last ? nB : cB + (size_t)(t + 2) * kstep;
;             const char* a3 = a2 + kstep; const char* b3 = b2 + kstep;
;     ...
;         for (int a = 0; a < 2; ++a)
; #pragma unroll
;             for (int b = 0; b < 2; ++b)
; #pragma unroll
;                 for (int m = 0; m < 4; ++m)
; #pragma unroll
;                     for (int n = 0; n < 2; ++n) acc[a][b][m][n] = (f32x4){0.f, 0.f, 0.f, 0.f};
.LBB0_807:
	s_ashr_i32 s23, s22, 31
	s_lshl_b64 s[36:37], s[22:23], 19
	s_add_u32 s36, s30, s36
	s_addc_u32 s37, s31, s37
	s_and_b64 s[38:39], s[6:7], exec
	s_cselect_b32 s23, s37, s45
	s_cselect_b32 s41, s36, s44
	s_ashr_i32 s21, s20, 31
	s_lshl_b64 s[38:39], s[20:21], 19
	s_add_u32 s38, s92, s38
	s_addc_u32 s39, s93, s39
	s_and_b64 s[48:49], s[6:7], exec
	s_cselect_b32 s21, s39, s47
	s_cselect_b32 s68, s38, s46
	s_add_u32 s44, s44, 0x40080
	s_addc_u32 s45, s45, 0
	s_add_u32 s69, s46, 0x100
	v_mov_b32_e32 v0, 0
	s_addc_u32 s70, s47, 0
	s_mov_b32 s71, -2
	s_waitcnt lgkmcnt(0)
	v_mov_b32_e32 v1, v0
	v_mov_b64_e32 v[2:3], 0
	v_mov_b64_e32 v[4:5], 0
	v_mov_b64_e32 v[6:7], 0
	v_mov_b64_e32 v[16:17], 0
	v_mov_b64_e32 v[18:19], 0
	v_mov_b64_e32 v[20:21], 0
	v_mov_b64_e32 v[22:23], 0
	v_mov_b64_e32 v[32:33], 0
	v_mov_b64_e32 v[34:35], 0
	v_mov_b64_e32 v[36:37], 0
	v_mov_b64_e32 v[38:39], 0
	v_mov_b64_e32 v[48:49], 0
	v_mov_b64_e32 v[50:51], 0
	v_mov_b64_e32 v[52:53], 0
	v_mov_b64_e32 v[54:55], 0
	v_mov_b64_e32 v[8:9], 0
	v_mov_b64_e32 v[10:11], 0
	v_mov_b64_e32 v[12:13], 0
	v_mov_b64_e32 v[14:15], 0
	v_mov_b64_e32 v[24:25], 0
	v_mov_b64_e32 v[26:27], 0
	v_mov_b64_e32 v[28:29], 0
	v_mov_b64_e32 v[30:31], 0
	v_mov_b64_e32 v[40:41], 0
	v_mov_b64_e32 v[42:43], 0
	v_mov_b64_e32 v[44:45], 0
	v_mov_b64_e32 v[46:47], 0
	v_mov_b64_e32 v[56:57], 0
	v_mov_b64_e32 v[58:59], 0
	v_mov_b64_e32 v[60:61], 0
	v_mov_b64_e32 v[62:63], 0
	v_mov_b64_e32 v[64:65], 0
	v_mov_b64_e32 v[66:67], 0
	v_mov_b64_e32 v[68:69], 0
	v_mov_b64_e32 v[70:71], 0
	v_mov_b64_e32 v[88:89], 0
	v_mov_b64_e32 v[90:91], 0
	v_mov_b64_e32 v[92:93], 0
	v_mov_b64_e32 v[94:95], 0
	v_mov_b64_e32 v[112:113], 0
	v_mov_b64_e32 v[114:115], 0
	v_mov_b64_e32 v[116:117], 0
	v_mov_b64_e32 v[118:119], 0
	v_mov_b64_e32 v[128:129], 0
	v_mov_b64_e32 v[130:131], 0
	v_mov_b64_e32 v[132:133], 0
	v_mov_b64_e32 v[134:135], 0
	v_mov_b64_e32 v[72:73], 0
	v_mov_b64_e32 v[74:75], 0
	v_mov_b64_e32 v[76:77], 0
	v_mov_b64_e32 v[78:79], 0
	v_mov_b64_e32 v[104:105], 0
	v_mov_b64_e32 v[106:107], 0
	v_mov_b64_e32 v[108:109], 0
	v_mov_b64_e32 v[110:111], 0
	v_mov_b64_e32 v[120:121], 0
	v_mov_b64_e32 v[122:123], 0
	v_mov_b64_e32 v[124:125], 0
	v_mov_b64_e32 v[126:127], 0
	v_mov_b64_e32 v[136:137], 0
	v_mov_b64_e32 v[138:139], 0
	v_mov_b64_e32 v[140:141], 0
	v_mov_b64_e32 v[142:143], 0
	.p2align	6

;     __device__ bool next(int i, Unit& u) const { if (i > 1 || !so.next(0, u)) return false; if (i == 1) { u.pm += 64; u.pn += 4; } return true; }
; template <class Epi, class Sched, bool ALIGN_EPI = false, bool SP2 = false>
; __device__ __forceinline__ void gemm_phase(PG8_LAS unsigned char* lds, const Gemm g, const Sched& S, const Epi& E) {
;     ...
;         const bool has_next = S.next(ui + 1, nxt);
;         const char* nA = has_next ? (const char*)g.A + (size_t)nxt.pm * tstep : cA; const char* nB = has_next ? (const char*)g.Bt + (size_t)nxt.pn * tstep : cB;
;         for (int t = 0; t < nt; t += 2) {
;             const bool last = (t == nt - 2);
;             const char* a1 = cA + (size_t)(t + 1) * kstep;
;             const char* a2 = last ? nA : cA + (size_t)(t + 2) * kstep; const char* b2 = last ? nB : cB + (size_t)(t + 2) * kstep;
;             const char* a3 = a2 + kstep; const char* b3 = b2 + kstep;
;     ...
;         for (int a = 0; a < 2; ++a)
; #pragma unroll
;             for (int b = 0; b < 2; ++b)
; #pragma unroll
;                 for (int m = 0; m < 4; ++m)
; #pragma unroll
;                     for (int n = 0; n < 2; ++n) acc[a][b][m][n] = (f32x4){0.f, 0.f, 0.f, 0.f};
.LBB0_906:
	s_ashr_i32 s23, s22, 31
	s_lshl_b64 s[28:29], s[22:23], 19
	s_add_u32 s28, s24, s28
	s_addc_u32 s29, s25, s29
	s_and_b64 s[38:39], s[4:5], exec
	s_cselect_b32 s23, s29, s37
	s_cselect_b32 s58, s28, s36
	s_ashr_i32 s21, s20, 31
	s_lshl_b64 s[38:39], s[20:21], 19
	v_lshl_add_u64 v[162:163], v[144:145], 0, s[38:39]
	v_cndmask_b32_e64 v128, v0, v162, s[4:5]
	s_add_u32 s36, s36, 0x40080
	v_lshl_add_u64 v[130:131], v[0:1], 0, s[18:19]
	v_mov_b32_e32 v0, 0
	v_cndmask_b32_e64 v129, v1, v163, s[4:5]
	s_addc_u32 s37, s37, 0
	s_mov_b32 s21, -2
	v_mov_b32_e32 v1, v0
	v_mov_b64_e32 v[2:3], 0
	v_mov_b64_e32 v[4:5], 0
	v_mov_b64_e32 v[6:7], 0
	v_mov_b64_e32 v[16:17], 0
	v_mov_b64_e32 v[18:19], 0
	v_mov_b64_e32 v[20:21], 0
	v_mov_b64_e32 v[22:23], 0
	v_mov_b64_e32 v[32:33], 0
	v_mov_b64_e32 v[34:35], 0
	v_mov_b64_e32 v[36:37], 0
	v_mov_b64_e32 v[38:39], 0
	v_mov_b64_e32 v[48:49], 0
	v_mov_b64_e32 v[50:51], 0
	v_mov_b64_e32 v[52:53], 0
	v_mov_b64_e32 v[54:55], 0
	v_mov_b64_e32 v[8:9], 0
	v_mov_b64_e32 v[10:11], 0
	v_mov_b64_e32 v[12:13], 0
	v_mov_b64_e32 v[14:15], 0
	v_mov_b64_e32 v[24:25], 0
	v_mov_b64_e32 v[26:27], 0
	v_mov_b64_e32 v[28:29], 0
	v_mov_b64_e32 v[30:31], 0
	v_mov_b64_e32 v[40:41], 0
	v_mov_b64_e32 v[42:43], 0
	v_mov_b64_e32 v[44:45], 0
	v_mov_b64_e32 v[46:47], 0
	v_mov_b64_e32 v[56:57], 0
	v_mov_b64_e32 v[58:59], 0
	v_mov_b64_e32 v[60:61], 0
	v_mov_b64_e32 v[62:63], 0
	v_mov_b64_e32 v[64:65], 0
	v_mov_b64_e32 v[66:67], 0
	v_mov_b64_e32 v[68:69], 0
	v_mov_b64_e32 v[70:71], 0
	v_mov_b64_e32 v[80:81], 0
	v_mov_b64_e32 v[82:83], 0
	v_mov_b64_e32 v[84:85], 0
	v_mov_b64_e32 v[86:87], 0
	v_mov_b64_e32 v[96:97], 0
	v_mov_b64_e32 v[98:99], 0
	v_mov_b64_e32 v[100:101], 0
	v_mov_b64_e32 v[102:103], 0
	v_mov_b64_e32 v[112:113], 0
	v_mov_b64_e32 v[114:115], 0
	v_mov_b64_e32 v[116:117], 0
	v_mov_b64_e32 v[118:119], 0
	v_mov_b64_e32 v[72:73], 0
	v_mov_b64_e32 v[74:75], 0
	v_mov_b64_e32 v[76:77], 0
	v_mov_b64_e32 v[78:79], 0
	v_mov_b64_e32 v[88:89], 0
	v_mov_b64_e32 v[90:91], 0
	v_mov_b64_e32 v[92:93], 0
	v_mov_b64_e32 v[94:95], 0
	v_mov_b64_e32 v[104:105], 0
	v_mov_b64_e32 v[106:107], 0
	v_mov_b64_e32 v[108:109], 0
	v_mov_b64_e32 v[110:111], 0
	v_mov_b64_e32 v[120:121], 0
	v_mov_b64_e32 v[122:123], 0
	v_mov_b64_e32 v[124:125], 0
	v_mov_b64_e32 v[126:127], 0
	.p2align	6

; template <class Epi, class Sched, bool ALIGN_EPI = false, bool SP2 = false>
; __device__ __forceinline__ void gemm_phase(PG8_LAS unsigned char* lds, const Gemm g, const Sched& S, const Epi& E) {
;     ...
;         for (int t = 0; t < nt; t += 2) {
;             const bool last = (t == nt - 2);
;             const char* a1 = cA + (size_t)(t + 1) * kstep;
;             const char* a2 = last ? nA : cA + (size_t)(t + 2) * kstep; const char* b2 = last ? nB : cB + (size_t)(t + 2) * kstep;
;             const char* a3 = a2 + kstep; const char* b3 = b2 + kstep;
;     ...
;         for (int a = 0; a < 2; ++a)
; #pragma unroll
;             for (int b = 0; b < 2; ++b)
; #pragma unroll
;                 for (int m = 0; m < 4; ++m)
; #pragma unroll
;                     for (int n = 0; n < 2; ++n) acc[a][b][m][n] = (f32x4){0.f, 0.f, 0.f, 0.f};
.LBB0_1006:
	s_add_u32 s22, s22, 0xb0080
	s_addc_u32 s23, s23, 0
	s_add_u32 s51, s26, 0x100
	v_mov_b32_e32 v0, 0
	s_addc_u32 s52, s27, 0
	s_mov_b32 s53, -2
	v_mov_b32_e32 v1, v0
	v_mov_b64_e32 v[2:3], 0
	v_mov_b64_e32 v[4:5], 0
	v_mov_b64_e32 v[6:7], 0
	v_mov_b64_e32 v[16:17], 0
	v_mov_b64_e32 v[18:19], 0
	v_mov_b64_e32 v[20:21], 0
	v_mov_b64_e32 v[22:23], 0
	v_mov_b64_e32 v[32:33], 0
	v_mov_b64_e32 v[34:35], 0
	v_mov_b64_e32 v[36:37], 0
	v_mov_b64_e32 v[38:39], 0
	v_mov_b64_e32 v[48:49], 0
	v_mov_b64_e32 v[50:51], 0
	v_mov_b64_e32 v[52:53], 0
	v_mov_b64_e32 v[54:55], 0
	v_mov_b64_e32 v[8:9], 0
	v_mov_b64_e32 v[10:11], 0
	v_mov_b64_e32 v[12:13], 0
	v_mov_b64_e32 v[14:15], 0
	v_mov_b64_e32 v[24:25], 0
	v_mov_b64_e32 v[26:27], 0
	v_mov_b64_e32 v[28:29], 0
	v_mov_b64_e32 v[30:31], 0
	v_mov_b64_e32 v[40:41], 0
	v_mov_b64_e32 v[42:43], 0
	v_mov_b64_e32 v[44:45], 0
	v_mov_b64_e32 v[46:47], 0
	v_mov_b64_e32 v[56:57], 0
	v_mov_b64_e32 v[58:59], 0
	v_mov_b64_e32 v[60:61], 0
	v_mov_b64_e32 v[62:63], 0
	v_mov_b64_e32 v[64:65], 0
	v_mov_b64_e32 v[66:67], 0
	v_mov_b64_e32 v[68:69], 0
	v_mov_b64_e32 v[70:71], 0
	v_mov_b64_e32 v[80:81], 0
	v_mov_b64_e32 v[82:83], 0
	v_mov_b64_e32 v[84:85], 0
	v_mov_b64_e32 v[86:87], 0
	v_mov_b64_e32 v[96:97], 0
	v_mov_b64_e32 v[98:99], 0
	v_mov_b64_e32 v[100:101], 0
	v_mov_b64_e32 v[102:103], 0
	v_mov_b64_e32 v[112:113], 0
	v_mov_b64_e32 v[114:115], 0
	v_mov_b64_e32 v[116:117], 0
	v_mov_b64_e32 v[118:119], 0
	v_mov_b64_e32 v[72:73], 0
	v_mov_b64_e32 v[74:75], 0
	v_mov_b64_e32 v[76:77], 0
	v_mov_b64_e32 v[78:79], 0
	v_mov_b64_e32 v[88:89], 0
	v_mov_b64_e32 v[90:91], 0
	v_mov_b64_e32 v[92:93], 0
	v_mov_b64_e32 v[94:95], 0
	v_mov_b64_e32 v[104:105], 0
	v_mov_b64_e32 v[106:107], 0
	v_mov_b64_e32 v[108:109], 0
	v_mov_b64_e32 v[110:111], 0
	v_mov_b64_e32 v[120:121], 0
	v_mov_b64_e32 v[122:123], 0
	v_mov_b64_e32 v[124:125], 0
	v_mov_b64_e32 v[126:127], 0
	.p2align	6
